# conv d-loops: s_setprio flips removed (A/B on top of v9)
# speedup vs baseline: 1.0035x; 1.0035x over previous
; #define CONV_TAIL() if (step + CONV_GRP < nsteps) CONV_STOREWIN(step + CONV_GRP); if ((step & 1) == 1 || step + 1 == nsteps) __syncthreads()
; #define CONV_DS(x) ({ int t_ = (x); LAUNDER_S(t_); t_; })
; __device__ __forceinline__ void conv_item(const Params& P, int slice, int item, LAS unsigned char* lds) {
;     ...
;     for (int d = CONV_DS(lo0); d < lo0 + hw; ++d) { CONV_HEADT(); CONV_TILESTEP(0, CONV_BPH(0, 0, d + 1), CONV_BPH(0, 1, d + 1), 1, CONV_WB(step + 1), 1, 1); CONV_TAIL(); }
.LBB0_399:
	s_add_i32 s68, s61, s16
	s_add_i32 s17, s68, -1
	v_lshl_add_u32 v240, v40, 1, v227
	global_load_dword v230, v240, s[8:9] offset:-2048
	global_load_dword v231, v240, s[8:9] offset:-1920
	global_load_dword v238, v240, s[8:9] offset:-1792
	global_load_dword v239, v240, s[8:9] offset:-1664
	v_add_u32_e32 v44, s30, v41
	s_and_b32 s0, s68, 7
	s_mulk_i32 s0, 0x1200
	s_waitcnt lgkmcnt(1)
	v_mfma_f32_16x16x32_bf16 v[12:15], v[88:91], v[144:147], v[12:15]
	v_mfma_f32_16x16x32_bf16 v[4:7], v[72:75], v[144:147], v[16:19]
	v_mfma_f32_16x16x32_bf16 v[16:19], v[64:67], v[144:147], v[20:23]
	v_mfma_f32_16x16x32_bf16 v[8:11], v[76:79], v[144:147], v[8:11]
	v_add_u32_e32 v51, s0, v243
	s_waitcnt lgkmcnt(6)
	v_mfma_f32_16x16x32_bf16 v[12:15], v[72:75], v[140:143], v[12:15]
	ds_read_b128 v[72:75], v51 offset:256
	v_mov_b32_e32 v45, s29
	v_cmp_gt_u32_e32 vcc, s61, v41
	v_cmp_gt_u32_e64 s[0:1], s61, v44
	s_nop 0
	v_cndmask_b32_e32 v50, v45, v43, vcc
	s_nop 0
	v_cndmask_b32_e64 v52, v45, v42, s[0:1]
	v_mfma_f32_16x16x32_bf16 v[4:7], v[56:59], v[140:143], v[4:7]
	v_mfma_f32_16x16x32_bf16 v[16:19], v[60:63], v[140:143], v[16:19]
	s_waitcnt lgkmcnt(4)
	v_mfma_f32_16x16x32_bf16 v[4:7], v[28:31], v[136:139], v[4:7]
	ds_read_b128 v[76:79], v51 offset:160
	ds_read_b128 v[88:91], v51 offset:192
	s_waitcnt lgkmcnt(3)
	ds_read_b128 v[116:119], v52 offset:192
	v_mfma_f32_16x16x32_bf16 v[20:23], v[24:27], v[136:139], v[16:19]
	s_nop 2
	v_mfma_f32_16x16x32_bf16 v[16:19], v[32:35], v[132:135], v[4:7]
	v_mfma_f32_16x16x32_bf16 v[8:11], v[64:67], v[140:143], v[8:11]
	v_mfma_f32_16x16x32_bf16 v[12:15], v[56:59], v[136:139], v[12:15]
	v_mfma_f32_16x16x32_bf16 v[8:11], v[60:63], v[136:139], v[8:11]
	ds_read_b128 v[136:139], v50 offset:128
	v_mfma_f32_16x16x32_bf16 v[12:15], v[28:31], v[132:135], v[12:15]
	v_mfma_f32_16x16x32_bf16 v[20:23], v[36:39], v[132:135], v[20:23]
	v_mfma_f32_16x16x32_bf16 v[8:11], v[24:27], v[132:135], v[8:11]
	ds_read_b128 v[32:35], v51 offset:448
	ds_read_b128 v[28:31], v51 offset:384
	ds_read_b128 v[36:39], v51 offset:416
	ds_read_b128 v[24:27], v51 offset:352
	ds_read_b128 v[60:63], v51 offset:288
	ds_read_b128 v[56:59], v51 offset:320
	ds_read_b128 v[132:135], v50 offset:192
	ds_read_b128 v[120:123], v52 offset:128
	ds_read_b128 v[140:143], v50 offset:64
	ds_read_b128 v[124:127], v52 offset:64
	ds_read_b128 v[64:67], v51 offset:224
	ds_read_b128 v[144:147], v50
	ds_read_b128 v[128:131], v52
	s_add_i32 s68, s68, 3
	s_cmp_ge_i32 s68, s87
	s_cbranch_scc1 .LBB0_401
	s_and_b32 s0, s68, 4
	s_and_b32 s1, s17, 3
	s_or_b32 s0, s0, s1
	s_mulk_i32 s0, 0x1200
	v_add_u32_e32 v44, s0, v157
	s_waitcnt vmcnt(0)
	ds_write2_b32 v44, v230, v231 offset1:32
	ds_write2_b32 v44, v238, v239 offset0:64 offset1:96

; #define CONV_TAIL() if (step + CONV_GRP < nsteps) CONV_STOREWIN(step + CONV_GRP); if ((step & 1) == 1 || step + 1 == nsteps) __syncthreads()
; #define CONV_DS(x) ({ int t_ = (x); LAUNDER_S(t_); t_; })
; __device__ __forceinline__ void conv_item(const Params& P, int slice, int item, LAS unsigned char* lds) {
;     ...
;     for (int d = CONV_DS(lo0 + hw); d < lo1; ++d) { CONV_HEADT(); CONV_TILESTEP(0, CONV_BPH(0, 0, d + 1), CONV_BPH(0, 1, d + 1), 1, CONV_WB(step + 1), 3, 1); CONV_TAIL(); }
.LBB0_407:
	s_add_i32 s68, s61, s16
	s_add_i32 s17, s68, -1
	v_lshl_add_u32 v240, v68, 1, v227
	global_load_dword v230, v240, s[8:9] offset:-2048
	global_load_dword v231, v240, s[8:9] offset:-1920
	global_load_dword v238, v240, s[8:9] offset:-1792
	global_load_dword v239, v240, s[8:9] offset:-1664
	v_add_u32_e32 v86, s30, v69
	s_and_b32 s0, s68, 7
	s_mulk_i32 s0, 0x1200
	s_waitcnt lgkmcnt(1)
	v_mfma_f32_16x16x32_bf16 v[0:3], v[72:75], v[144:147], v[16:19]
	v_mfma_f32_16x16x32_bf16 v[4:7], v[64:67], v[144:147], v[20:23]
	v_mfma_f32_16x16x32_bf16 v[12:15], v[88:91], v[144:147], v[12:15]
	v_mfma_f32_16x16x32_bf16 v[8:11], v[76:79], v[144:147], v[8:11]
	s_waitcnt lgkmcnt(0)
	v_mfma_f32_16x16x32_bf16 v[16:19], v[72:75], v[128:131], v[52:55]
	v_mfma_f32_16x16x32_bf16 v[0:3], v[56:59], v[140:143], v[0:3]
	v_mfma_f32_16x16x32_bf16 v[16:19], v[56:59], v[124:127], v[16:19]
	v_mfma_f32_16x16x32_bf16 v[0:3], v[28:31], v[136:139], v[0:3]
	v_mfma_f32_16x16x32_bf16 v[20:23], v[28:31], v[120:123], v[16:19]
	v_mfma_f32_16x16x32_bf16 v[16:19], v[32:35], v[132:135], v[0:3]
	v_mfma_f32_16x16x32_bf16 v[52:55], v[32:35], v[116:119], v[20:23]
	v_mfma_f32_16x16x32_bf16 v[20:23], v[64:67], v[128:131], v[48:51]
	s_nop 3
	v_mfma_f32_16x16x32_bf16 v[44:47], v[88:91], v[128:131], v[44:47]
	v_mfma_f32_16x16x32_bf16 v[12:15], v[72:75], v[140:143], v[12:15]
	v_mfma_f32_16x16x32_bf16 v[44:47], v[72:75], v[124:127], v[44:47]
	v_mfma_f32_16x16x32_bf16 v[40:43], v[76:79], v[128:131], v[40:43]
	v_mov_b32_e32 v72, s29
	v_mfma_f32_16x16x32_bf16 v[12:15], v[56:59], v[136:139], v[12:15]
	v_mfma_f32_16x16x32_bf16 v[44:47], v[56:59], v[120:123], v[44:47]
	v_mfma_f32_16x16x32_bf16 v[2:5], v[60:63], v[140:143], v[4:7]
	v_mfma_f32_16x16x32_bf16 v[20:23], v[60:63], v[124:127], v[20:23]
	v_mfma_f32_16x16x32_bf16 v[2:5], v[24:27], v[136:139], v[2:5]
	v_mfma_f32_16x16x32_bf16 v[48:51], v[24:27], v[120:123], v[20:23]
	v_mfma_f32_16x16x32_bf16 v[20:23], v[36:39], v[132:135], v[2:5]
	v_mfma_f32_16x16x32_bf16 v[2:5], v[64:67], v[140:143], v[8:11]
	v_mfma_f32_16x16x32_bf16 v[6:9], v[64:67], v[124:127], v[40:43]
	v_mfma_f32_16x16x32_bf16 v[2:5], v[60:63], v[136:139], v[2:5]
	v_mfma_f32_16x16x32_bf16 v[40:43], v[60:63], v[120:123], v[6:9]
	v_mfma_f32_16x16x32_bf16 v[8:11], v[24:27], v[132:135], v[2:5]
	s_nop 5
	v_cmp_gt_u32_e32 vcc, s61, v69
	s_nop 0
	s_nop 0
	v_cndmask_b32_e32 v82, v72, v71, vcc
	ds_read_b128 v[136:139], v82 offset:128
	v_add_u32_e32 v87, s0, v243
	v_cmp_gt_u32_e64 s[0:1], s61, v86
	s_nop 1
	v_cndmask_b32_e64 v74, v72, v70, s[0:1]
	ds_read_b128 v[88:91], v87 offset:192
	ds_read_b128 v[124:127], v74 offset:64
	ds_read_b128 v[120:123], v74 offset:128
	ds_read_b128 v[128:131], v74
	v_mfma_f32_16x16x32_bf16 v[44:47], v[28:31], v[116:119], v[44:47]
	v_mfma_f32_16x16x32_bf16 v[48:51], v[36:39], v[116:119], v[48:51]
	v_mfma_f32_16x16x32_bf16 v[40:43], v[24:27], v[116:119], v[40:43]
	ds_read_b128 v[116:119], v74 offset:192
	ds_read_b128 v[72:75], v87 offset:256
	ds_read_b128 v[32:35], v87 offset:448
	ds_read_b128 v[76:79], v87 offset:160
	v_mfma_f32_16x16x32_bf16 v[12:15], v[28:31], v[132:135], v[12:15]
	ds_read_b128 v[28:31], v87 offset:384
	ds_read_b128 v[144:147], v82
	ds_read_b128 v[140:143], v82 offset:64
	ds_read_b128 v[64:67], v87 offset:224
	ds_read_b128 v[36:39], v87 offset:416
	ds_read_b128 v[24:27], v87 offset:352
	ds_read_b128 v[132:135], v82 offset:192
	ds_read_b128 v[60:63], v87 offset:288
	ds_read_b128 v[56:59], v87 offset:320
	s_add_i32 s68, s68, 3
	s_cmp_ge_i32 s68, s87
	s_cbranch_scc1 .LBB0_409
	s_and_b32 s0, s68, 4
	s_and_b32 s1, s17, 3
	s_or_b32 s0, s0, s1
	s_mulk_i32 s0, 0x1200
	v_add_u32_e32 v80, s0, v157
	s_waitcnt vmcnt(0)
	ds_write2_b32 v80, v230, v231 offset1:32
	ds_write2_b32 v80, v238, v239 offset0:64 offset1:96

; #define CONV_TAIL() if (step + CONV_GRP < nsteps) CONV_STOREWIN(step + CONV_GRP); if ((step & 1) == 1 || step + 1 == nsteps) __syncthreads()
; #define CONV_DS(x) ({ int t_ = (x); LAUNDER_S(t_); t_; })
; #define CONV_NB1(H) ((d + 1 <= hi0) ? CONV_BPH(0, H, d + 1) : CONV_BPH(1, H, d + 1))
; __device__ __forceinline__ void conv_item(const Params& P, int slice, int item, LAS unsigned char* lds) {
;     ...
;     for (int d = CONV_DS(lo1); d < lo1 + hw; ++d) { CONV_HEADT(); CONV_TILESTEP(0, CONV_BPH(1, 0, d), CONV_BPH(1, 1, d), 0, Wn, 3, 1);
;       CONV_TILESTEP(1, CONV_NB1(0), CONV_NB1(1), 1, CONV_WB(step + 1), 1, 0); CONV_TAIL(); }
.LBB0_415:
	v_lshl_add_u32 v240, v100, 1, v227
	global_load_dword v230, v240, s[8:9] offset:-2048
	global_load_dword v231, v240, s[8:9] offset:-1920
	global_load_dword v238, v240, s[8:9] offset:-1792
	global_load_dword v239, v240, s[8:9] offset:-1664
	v_add3_u32 v83, v247, s17, 1
	s_add_i32 s69, s61, s16
	s_add_i32 s68, s69, -1
	s_waitcnt lgkmcnt(1)
	v_mfma_f32_16x16x32_bf16 v[2:5], v[72:75], v[144:147], v[16:19]
	v_mfma_f32_16x16x32_bf16 v[16:19], v[64:67], v[144:147], v[20:23]
	v_mfma_f32_16x16x32_bf16 v[12:15], v[88:91], v[144:147], v[12:15]
	v_mfma_f32_16x16x32_bf16 v[6:9], v[76:79], v[144:147], v[8:11]
	s_waitcnt lgkmcnt(0)
	v_mfma_f32_16x16x32_bf16 v[20:23], v[72:75], v[128:131], v[52:55]
	v_mfma_f32_16x16x32_bf16 v[48:51], v[64:67], v[128:131], v[48:51]
	v_mfma_f32_16x16x32_bf16 v[44:47], v[88:91], v[128:131], v[44:47]
	v_mfma_f32_16x16x32_bf16 v[40:43], v[76:79], v[128:131], v[40:43]
	v_mfma_f32_16x16x32_bf16 v[52:55], v[56:59], v[140:143], v[2:5]
	v_mfma_f32_16x16x32_bf16 v[4:7], v[64:67], v[140:143], v[6:9]
	v_mfma_f32_16x16x32_bf16 v[20:23], v[56:59], v[124:127], v[20:23]
	v_mfma_f32_16x16x32_bf16 v[10:13], v[72:75], v[140:143], v[12:15]
	v_mfma_f32_16x16x32_bf16 v[48:51], v[60:63], v[124:127], v[48:51]
	v_mfma_f32_16x16x32_bf16 v[44:47], v[72:75], v[124:127], v[44:47]
	v_mfma_f32_16x16x32_bf16 v[40:43], v[64:67], v[124:127], v[40:43]
	v_mfma_f32_16x16x32_bf16 v[106:109], v[60:63], v[136:139], v[4:7]
	v_cmp_gt_u32_e32 vcc, s61, v83
	v_mov_b32_e32 v83, s29
	s_nop 0
	v_cndmask_b32_e32 v130, v83, v82, vcc
	v_mfma_f32_16x16x32_bf16 v[16:19], v[60:63], v[140:143], v[16:19]
	v_mfma_f32_16x16x32_bf16 v[52:55], v[28:31], v[136:139], v[52:55]
	v_mfma_f32_16x16x32_bf16 v[48:51], v[24:27], v[120:123], v[48:51]
	v_mfma_f32_16x16x32_bf16 v[44:47], v[56:59], v[120:123], v[44:47]
	v_mfma_f32_16x16x32_bf16 v[8:11], v[56:59], v[136:139], v[10:13]
	v_mfma_f32_16x16x32_bf16 v[12:15], v[28:31], v[132:135], v[8:11]
	v_mfma_f32_16x16x32_bf16 v[8:11], v[24:27], v[132:135], v[106:109]
	s_nop 2
	ds_read_b128 v[106:109], v130 offset:64
	v_mfma_f32_16x16x32_bf16 v[102:105], v[24:27], v[136:139], v[16:19]
	v_mfma_f32_16x16x32_bf16 v[124:127], v[28:31], v[120:123], v[20:23]
	v_mfma_f32_16x16x32_bf16 v[40:43], v[60:63], v[120:123], v[40:43]
	ds_read_b128 v[110:113], v130 offset:128
	v_mfma_f32_16x16x32_bf16 v[16:19], v[32:35], v[132:135], v[52:55]
	v_mfma_f32_16x16x32_bf16 v[20:23], v[36:39], v[132:135], v[102:105]
	ds_read_b128 v[120:123], v130 offset:192
	v_mfma_f32_16x16x32_bf16 v[52:55], v[32:35], v[116:119], v[124:127]
	v_mfma_f32_16x16x32_bf16 v[48:51], v[36:39], v[116:119], v[48:51]
	v_mfma_f32_16x16x32_bf16 v[44:47], v[28:31], v[116:119], v[44:47]
	v_mfma_f32_16x16x32_bf16 v[40:43], v[24:27], v[116:119], v[40:43]
	ds_read_b128 v[102:105], v130
	s_cmp_lt_i32 s16, s26
	s_cselect_b64 vcc, -1, 0
	v_cndmask_b32_e32 v80, v247, v242, vcc
	v_add_u32_e32 v80, s17, v80
	v_cndmask_b32_e32 v101, v248, v245, vcc
	v_cmp_gt_u32_e64 s[0:1], s61, v80
	v_mad_u64_u32 v[114:115], s[70:71], v80, s85, v[156:157]
	v_add_u32_e32 v101, s17, v101
	v_cndmask_b32_e64 v80, v83, v114, s[0:1]
	v_mad_u64_u32 v[114:115], s[0:1], v101, s85, v[156:157]
	s_and_b32 s0, s69, 7
	v_cmp_gt_u32_e32 vcc, s61, v101
	s_mulk_i32 s0, 0x1200
	v_add_u32_e32 v101, s0, v243
	v_cndmask_b32_e32 v83, v83, v114, vcc
	s_waitcnt lgkmcnt(0)
	v_mfma_f32_16x16x32_bf16 v[92:95], v[72:75], v[102:105], v[92:95]
	v_mfma_f32_16x16x32_bf16 v[96:99], v[64:67], v[102:105], v[96:99]
	v_mfma_f32_16x16x32_bf16 v[84:87], v[88:91], v[102:105], v[84:87]
	v_mfma_f32_16x16x32_bf16 v[68:71], v[76:79], v[102:105], v[68:71]
	ds_read_b128 v[144:147], v80
	v_mfma_f32_16x16x32_bf16 v[92:95], v[56:59], v[106:109], v[92:95]
	v_mfma_f32_16x16x32_bf16 v[96:99], v[60:63], v[106:109], v[96:99]
	v_mfma_f32_16x16x32_bf16 v[72:75], v[72:75], v[106:109], v[84:87]
	v_mfma_f32_16x16x32_bf16 v[64:67], v[64:67], v[106:109], v[68:71]
	ds_read_b128 v[128:131], v83
	ds_read_b128 v[76:79], v101 offset:160
	ds_read_b128 v[88:91], v101 offset:192
	v_mfma_f32_16x16x32_bf16 v[68:71], v[28:31], v[110:113], v[92:95]
	v_mfma_f32_16x16x32_bf16 v[84:87], v[24:27], v[110:113], v[96:99]
	v_mfma_f32_16x16x32_bf16 v[56:59], v[56:59], v[110:113], v[72:75]
	v_mfma_f32_16x16x32_bf16 v[60:63], v[60:63], v[110:113], v[64:67]
	ds_read_b128 v[140:143], v80 offset:64
	v_mfma_f32_16x16x32_bf16 v[92:95], v[32:35], v[120:123], v[68:71]
	v_mfma_f32_16x16x32_bf16 v[96:99], v[36:39], v[120:123], v[84:87]
	v_mfma_f32_16x16x32_bf16 v[84:87], v[28:31], v[120:123], v[56:59]
	v_mfma_f32_16x16x32_bf16 v[68:71], v[24:27], v[120:123], v[60:63]
	ds_read_b128 v[124:127], v83 offset:64
	ds_read_b128 v[64:67], v101 offset:224
	ds_read_b128 v[72:75], v101 offset:256
	ds_read_b128 v[136:139], v80 offset:128
	ds_read_b128 v[120:123], v83 offset:128
	ds_read_b128 v[60:63], v101 offset:288
	ds_read_b128 v[56:59], v101 offset:320
	ds_read_b128 v[132:135], v80 offset:192
	ds_read_b128 v[116:119], v83 offset:192
	ds_read_b128 v[24:27], v101 offset:352
	ds_read_b128 v[28:31], v101 offset:384
	ds_read_b128 v[36:39], v101 offset:416
	ds_read_b128 v[32:35], v101 offset:448
	s_add_i32 s0, s69, 3
	s_cmp_ge_i32 s0, s87
	s_cbranch_scc1 .LBB0_417
	s_and_b32 s0, s0, 4
	s_and_b32 s1, s68, 3
	s_or_b32 s0, s0, s1
	s_mulk_i32 s0, 0x1200
	v_add_u32_e32 v80, s0, v157
	s_waitcnt vmcnt(0)
	ds_write2_b32 v80, v230, v231 offset1:32
	ds_write2_b32 v80, v238, v239 offset0:64 offset1:96

; #define CONV_TAIL() if (step + CONV_GRP < nsteps) CONV_STOREWIN(step + CONV_GRP); if ((step & 1) == 1 || step + 1 == nsteps) __syncthreads()
; #define CONV_DS(x) ({ int t_ = (x); LAUNDER_S(t_); t_; })
; #define CONV_NB1(H) ((d + 1 <= hi0) ? CONV_BPH(0, H, d + 1) : CONV_BPH(1, H, d + 1))
; __device__ __forceinline__ void conv_item(const Params& P, int slice, int item, LAS unsigned char* lds) {
;     ...
;     for (int d = CONV_DS(lo1 + hw); d <= hi0 - hw; ++d) { CONV_HEADT(); CONV_TILESTEP(0, CONV_BPH(1, 0, d), CONV_BPH(1, 1, d), 0, Wn, 3, 1);
;       CONV_TILESTEP(1, CONV_NB1(0), CONV_NB1(1), 1, CONV_WB(step + 1), 3, 0); CONV_TAIL(); }
.LBB0_422:
	s_add_i32 s68, s17, 1
	v_lshl_add_u32 v240, v150, 1, v227
	global_load_dword v230, v240, s[8:9] offset:-2048
	global_load_dword v231, v240, s[8:9] offset:-1920
	global_load_dword v238, v240, s[8:9] offset:-1792
	global_load_dword v239, v240, s[8:9] offset:-1664
	v_add3_u32 v83, v247, s16, 1
	v_add3_u32 v149, v248, s16, 1
	s_add_i32 s69, s61, s17
	s_waitcnt lgkmcnt(1)
	v_mfma_f32_16x16x32_bf16 v[16:19], v[72:75], v[144:147], v[16:19]
	v_mfma_f32_16x16x32_bf16 v[20:23], v[64:67], v[144:147], v[20:23]
	v_mfma_f32_16x16x32_bf16 v[12:15], v[88:91], v[144:147], v[12:15]
	v_mfma_f32_16x16x32_bf16 v[8:11], v[76:79], v[144:147], v[8:11]
	s_waitcnt lgkmcnt(0)
	v_mfma_f32_16x16x32_bf16 v[52:55], v[72:75], v[128:131], v[52:55]
	v_mfma_f32_16x16x32_bf16 v[48:51], v[64:67], v[128:131], v[48:51]
	v_mfma_f32_16x16x32_bf16 v[44:47], v[88:91], v[128:131], v[44:47]
	v_mfma_f32_16x16x32_bf16 v[40:43], v[76:79], v[128:131], v[40:43]
	v_mfma_f32_16x16x32_bf16 v[40:43], v[64:67], v[124:127], v[40:43]
	v_mfma_f32_16x16x32_bf16 v[40:43], v[60:63], v[120:123], v[40:43]
	v_mfma_f32_16x16x32_bf16 v[40:43], v[24:27], v[116:119], v[40:43]
	v_mfma_f32_16x16x32_bf16 v[44:47], v[72:75], v[124:127], v[44:47]
	v_mfma_f32_16x16x32_bf16 v[44:47], v[56:59], v[120:123], v[44:47]
	v_mfma_f32_16x16x32_bf16 v[44:47], v[28:31], v[116:119], v[44:47]
	v_mfma_f32_16x16x32_bf16 v[48:51], v[60:63], v[124:127], v[48:51]
	v_mfma_f32_16x16x32_bf16 v[48:51], v[24:27], v[120:123], v[48:51]
	v_mfma_f32_16x16x32_bf16 v[48:51], v[36:39], v[116:119], v[48:51]
	v_mfma_f32_16x16x32_bf16 v[52:55], v[56:59], v[124:127], v[52:55]
	v_mfma_f32_16x16x32_bf16 v[52:55], v[28:31], v[120:123], v[52:55]
	v_mfma_f32_16x16x32_bf16 v[52:55], v[32:35], v[116:119], v[52:55]
	v_mov_b32_e32 v80, s29
	v_cmp_gt_u32_e32 vcc, s61, v83
	s_nop 1
	v_cndmask_b32_e32 v83, v80, v148, vcc
	v_cmp_gt_u32_e32 vcc, s61, v149
	s_nop 1
	v_cndmask_b32_e32 v149, v80, v82, vcc
	ds_read_b128 v[116:119], v149 offset:192
	v_mfma_f32_16x16x32_bf16 v[8:11], v[64:67], v[140:143], v[8:11]
	v_mfma_f32_16x16x32_bf16 v[16:19], v[56:59], v[140:143], v[16:19]
	v_mfma_f32_16x16x32_bf16 v[20:23], v[60:63], v[140:143], v[20:23]
	v_mfma_f32_16x16x32_bf16 v[12:15], v[72:75], v[140:143], v[12:15]
	v_mfma_f32_16x16x32_bf16 v[8:11], v[60:63], v[136:139], v[8:11]
	v_mfma_f32_16x16x32_bf16 v[8:11], v[24:27], v[132:135], v[8:11]
	v_mfma_f32_16x16x32_bf16 v[12:15], v[56:59], v[136:139], v[12:15]
	v_mfma_f32_16x16x32_bf16 v[12:15], v[28:31], v[132:135], v[12:15]
	v_mfma_f32_16x16x32_bf16 v[20:23], v[24:27], v[136:139], v[20:23]
	v_mfma_f32_16x16x32_bf16 v[20:23], v[36:39], v[132:135], v[20:23]
	v_mfma_f32_16x16x32_bf16 v[16:19], v[28:31], v[136:139], v[16:19]
	v_mfma_f32_16x16x32_bf16 v[16:19], v[32:35], v[132:135], v[16:19]
	ds_read_b128 v[132:135], v83 offset:192
	ds_read_b128 v[120:123], v149 offset:128
	ds_read_b128 v[136:139], v83 offset:128
	ds_read_b128 v[124:127], v149 offset:64
	ds_read_b128 v[140:143], v83 offset:64
	ds_read_b128 v[128:131], v149
	ds_read_b128 v[144:147], v83
	s_cmp_lt_i32 s68, s26
	s_cselect_b64 vcc, -1, 0
	v_cndmask_b32_e32 v83, v247, v242, vcc
	v_add_u32_e32 v83, s16, v83
	v_cndmask_b32_e32 v149, v248, v245, vcc
	v_cmp_gt_u32_e64 s[0:1], s61, v83
	v_mad_u64_u32 v[152:153], s[70:71], v83, s85, v[156:157]
	v_add_u32_e32 v149, s16, v149
	v_cndmask_b32_e64 v83, v80, v152, s[0:1]
	v_mad_u64_u32 v[152:153], s[0:1], v149, s85, v[156:157]
	s_add_i32 s0, s69, 1
	s_and_b32 s0, s0, 7
	v_cmp_gt_u32_e32 vcc, s61, v149
	s_mulk_i32 s0, 0x1200
	v_add_u32_e32 v149, s0, v243
	v_cndmask_b32_e32 v80, v80, v152, vcc
	s_waitcnt lgkmcnt(0)
	v_mfma_f32_16x16x32_bf16 v[92:95], v[72:75], v[144:147], v[92:95]
	v_mfma_f32_16x16x32_bf16 v[96:99], v[64:67], v[144:147], v[96:99]
	v_mfma_f32_16x16x32_bf16 v[84:87], v[88:91], v[144:147], v[84:87]
	v_mfma_f32_16x16x32_bf16 v[68:71], v[76:79], v[144:147], v[68:71]
	ds_read_b128 v[144:147], v83
	v_mfma_f32_16x16x32_bf16 v[112:115], v[72:75], v[128:131], v[112:115]
	v_mfma_f32_16x16x32_bf16 v[108:111], v[64:67], v[128:131], v[108:111]
	v_mfma_f32_16x16x32_bf16 v[104:107], v[88:91], v[128:131], v[104:107]
	v_mfma_f32_16x16x32_bf16 v[100:103], v[76:79], v[128:131], v[100:103]
	ds_read_b128 v[128:131], v80
	ds_read_b128 v[76:79], v149 offset:160
	ds_read_b128 v[88:91], v149 offset:192
	v_mfma_f32_16x16x32_bf16 v[92:95], v[56:59], v[140:143], v[92:95]
	v_mfma_f32_16x16x32_bf16 v[96:99], v[60:63], v[140:143], v[96:99]
	v_mfma_f32_16x16x32_bf16 v[84:87], v[72:75], v[140:143], v[84:87]
	v_mfma_f32_16x16x32_bf16 v[68:71], v[64:67], v[140:143], v[68:71]
	ds_read_b128 v[140:143], v83 offset:64
	v_mfma_f32_16x16x32_bf16 v[112:115], v[56:59], v[124:127], v[112:115]
	v_mfma_f32_16x16x32_bf16 v[108:111], v[60:63], v[124:127], v[108:111]
	v_mfma_f32_16x16x32_bf16 v[104:107], v[72:75], v[124:127], v[104:107]
	v_mfma_f32_16x16x32_bf16 v[100:103], v[64:67], v[124:127], v[100:103]
	ds_read_b128 v[124:127], v80 offset:64
	ds_read_b128 v[64:67], v149 offset:224
	ds_read_b128 v[72:75], v149 offset:256
	v_mfma_f32_16x16x32_bf16 v[92:95], v[28:31], v[136:139], v[92:95]
	v_mfma_f32_16x16x32_bf16 v[96:99], v[24:27], v[136:139], v[96:99]
	v_mfma_f32_16x16x32_bf16 v[84:87], v[56:59], v[136:139], v[84:87]
	v_mfma_f32_16x16x32_bf16 v[68:71], v[60:63], v[136:139], v[68:71]
	ds_read_b128 v[136:139], v83 offset:128
	v_mfma_f32_16x16x32_bf16 v[112:115], v[28:31], v[120:123], v[112:115]
	v_mfma_f32_16x16x32_bf16 v[108:111], v[24:27], v[120:123], v[108:111]
	v_mfma_f32_16x16x32_bf16 v[104:107], v[56:59], v[120:123], v[104:107]
	v_mfma_f32_16x16x32_bf16 v[100:103], v[60:63], v[120:123], v[100:103]
	ds_read_b128 v[120:123], v80 offset:128
	ds_read_b128 v[60:63], v149 offset:288
	ds_read_b128 v[56:59], v149 offset:320
	v_mfma_f32_16x16x32_bf16 v[92:95], v[32:35], v[132:135], v[92:95]
	v_mfma_f32_16x16x32_bf16 v[96:99], v[36:39], v[132:135], v[96:99]
	v_mfma_f32_16x16x32_bf16 v[84:87], v[28:31], v[132:135], v[84:87]
	v_mfma_f32_16x16x32_bf16 v[68:71], v[24:27], v[132:135], v[68:71]
	ds_read_b128 v[132:135], v83 offset:192
	v_mfma_f32_16x16x32_bf16 v[112:115], v[32:35], v[116:119], v[112:115]
	v_mfma_f32_16x16x32_bf16 v[108:111], v[36:39], v[116:119], v[108:111]
	v_mfma_f32_16x16x32_bf16 v[104:107], v[28:31], v[116:119], v[104:107]
	v_mfma_f32_16x16x32_bf16 v[100:103], v[24:27], v[116:119], v[100:103]
	ds_read_b128 v[116:119], v80 offset:192
	ds_read_b128 v[24:27], v149 offset:352
	ds_read_b128 v[28:31], v149 offset:384
	ds_read_b128 v[36:39], v149 offset:416
	ds_read_b128 v[32:35], v149 offset:448
	s_add_i32 s0, s69, 4
	s_cmp_ge_i32 s0, s87
	s_cbranch_scc1 .LBB0_424
	s_and_b32 s0, s0, 4
	s_and_b32 s1, s69, 3
	s_or_b32 s0, s0, s1
	s_mulk_i32 s0, 0x1200
	v_add_u32_e32 v80, s0, v157
	s_waitcnt vmcnt(0)
	ds_write2_b32 v80, v230, v231 offset1:32
	ds_write2_b32 v80, v238, v239 offset0:64 offset1:96

; #define CONV_TAIL() if (step + CONV_GRP < nsteps) CONV_STOREWIN(step + CONV_GRP); if ((step & 1) == 1 || step + 1 == nsteps) __syncthreads()
; #define CONV_DS(x) ({ int t_ = (x); LAUNDER_S(t_); t_; })
; #define CONV_NB1(H) ((d + 1 <= hi0) ? CONV_BPH(0, H, d + 1) : CONV_BPH(1, H, d + 1))
; __device__ __forceinline__ void conv_item(const Params& P, int slice, int item, LAS unsigned char* lds) {
;     ...
;     for (int d = CONV_DS(hi0 - hw + 1); d <= hi0; ++d) { CONV_HEADT(); CONV_TILESTEP(0, CONV_BPH(1, 0, d), CONV_BPH(1, 1, d), 0, Wn, 2, 1);
;       CONV_TILESTEP(1, CONV_NB1(0), CONV_NB1(1), 1, CONV_WB(step + 1), 3, 0); CONV_TAIL(); }
.LBB0_432:
	v_lshl_add_u32 v240, v233, 1, v227
	global_load_dword v230, v240, s[8:9] offset:-2048
	global_load_dword v231, v240, s[8:9] offset:-1920
	global_load_dword v238, v240, s[8:9] offset:-1792
	global_load_dword v239, v240, s[8:9] offset:-1664
	v_add3_u32 v1, v247, s69, 1
	v_add3_u32 v6, v248, s69, 1
	s_add_i32 s71, s61, s68
	s_add_i32 s70, s71, -1
	s_waitcnt lgkmcnt(0)
	v_mfma_f32_16x16x32_bf16 v[2:5], v[72:75], v[128:131], v[52:55]
	v_mfma_f32_16x16x32_bf16 v[48:51], v[64:67], v[128:131], v[48:51]
	v_mfma_f32_16x16x32_bf16 v[44:47], v[88:91], v[128:131], v[44:47]
	v_mfma_f32_16x16x32_bf16 v[40:43], v[76:79], v[128:131], v[40:43]
	v_mov_b32_e32 v83, s29
	v_cmp_gt_u32_e32 vcc, s61, v1
	s_nop 1
	v_cndmask_b32_e32 v130, v83, v216, vcc
	v_cmp_gt_u32_e32 vcc, s61, v6
	s_nop 1
	v_cndmask_b32_e32 v138, v83, v82, vcc
	v_mfma_f32_16x16x32_bf16 v[2:5], v[56:59], v[124:127], v[2:5]
	v_mfma_f32_16x16x32_bf16 v[48:51], v[60:63], v[124:127], v[48:51]
	v_mfma_f32_16x16x32_bf16 v[44:47], v[72:75], v[124:127], v[44:47]
	v_mfma_f32_16x16x32_bf16 v[40:43], v[64:67], v[124:127], v[40:43]
	v_mfma_f32_16x16x32_bf16 v[48:51], v[24:27], v[120:123], v[48:51]
	v_mfma_f32_16x16x32_bf16 v[44:47], v[56:59], v[120:123], v[44:47]
	v_mfma_f32_16x16x32_bf16 v[40:43], v[60:63], v[120:123], v[40:43]
	v_mfma_f32_16x16x32_bf16 v[48:51], v[36:39], v[116:119], v[48:51]
	ds_read_b128 v[148:151], v138 offset:192
	v_mfma_f32_16x16x32_bf16 v[4:7], v[28:31], v[120:123], v[2:5]
	v_mfma_f32_16x16x32_bf16 v[44:47], v[28:31], v[116:119], v[44:47]
	v_mfma_f32_16x16x32_bf16 v[40:43], v[24:27], v[116:119], v[40:43]
	s_nop 0
	v_mfma_f32_16x16x32_bf16 v[52:55], v[32:35], v[116:119], v[4:7]
	ds_read_b128 v[116:119], v138 offset:128
	ds_read_b128 v[124:127], v138 offset:64
	ds_read_b128 v[136:139], v138
	ds_read_b128 v[132:135], v130 offset:64
	ds_read_b128 v[152:155], v130 offset:192
	ds_read_b128 v[120:123], v130 offset:128
	ds_read_b128 v[128:131], v130
	s_cmp_ge_i32 s68, s26
	s_cselect_b64 s[16:17], -1, 0
	s_cmp_lt_i32 s68, s26
	s_cselect_b64 vcc, -1, 0
	v_cndmask_b32_e32 v80, v247, v242, vcc
	v_add_u32_e32 v80, s69, v80
	v_cmp_gt_u32_e64 s[0:1], s61, v80
	v_mad_u64_u32 v[140:141], s[72:73], v80, s85, v[156:157]
	s_nop 0
	v_cndmask_b32_e64 v80, v83, v140, s[0:1]
	v_cndmask_b32_e32 v140, v248, v245, vcc
	v_add_u32_e32 v140, s69, v140
	v_cmp_gt_u32_e32 vcc, s61, v140
	v_mad_u64_u32 v[140:141], s[0:1], v140, s85, v[156:157]
	s_and_b32 s0, s71, 7
	s_mulk_i32 s0, 0x1200
	v_cndmask_b32_e32 v83, v83, v140, vcc
	v_add_u32_e32 v217, s0, v243
	s_waitcnt lgkmcnt(0)
	v_mfma_f32_16x16x32_bf16 v[92:95], v[72:75], v[128:131], v[92:95]
	v_mfma_f32_16x16x32_bf16 v[96:99], v[64:67], v[128:131], v[96:99]
	v_mfma_f32_16x16x32_bf16 v[84:87], v[88:91], v[128:131], v[84:87]
	v_mfma_f32_16x16x32_bf16 v[68:71], v[76:79], v[128:131], v[68:71]
	ds_read_b128 v[144:147], v80
	v_mfma_f32_16x16x32_bf16 v[112:115], v[72:75], v[136:139], v[112:115]
	v_mfma_f32_16x16x32_bf16 v[108:111], v[64:67], v[136:139], v[108:111]
	v_mfma_f32_16x16x32_bf16 v[104:107], v[88:91], v[136:139], v[104:107]
	v_mfma_f32_16x16x32_bf16 v[100:103], v[76:79], v[136:139], v[100:103]
	ds_read_b128 v[128:131], v83
	ds_read_b128 v[76:79], v217 offset:160
	ds_read_b128 v[88:91], v217 offset:192
	v_mfma_f32_16x16x32_bf16 v[92:95], v[56:59], v[132:135], v[92:95]
	v_mfma_f32_16x16x32_bf16 v[96:99], v[60:63], v[132:135], v[96:99]
	v_mfma_f32_16x16x32_bf16 v[84:87], v[72:75], v[132:135], v[84:87]
	v_mfma_f32_16x16x32_bf16 v[68:71], v[64:67], v[132:135], v[68:71]
	ds_read_b128 v[140:143], v80 offset:64
	v_mfma_f32_16x16x32_bf16 v[112:115], v[56:59], v[124:127], v[112:115]
	v_mfma_f32_16x16x32_bf16 v[108:111], v[60:63], v[124:127], v[108:111]
	v_mfma_f32_16x16x32_bf16 v[104:107], v[72:75], v[124:127], v[104:107]
	v_mfma_f32_16x16x32_bf16 v[100:103], v[64:67], v[124:127], v[100:103]
	ds_read_b128 v[124:127], v83 offset:64
	ds_read_b128 v[64:67], v217 offset:224
	ds_read_b128 v[72:75], v217 offset:256
	v_mfma_f32_16x16x32_bf16 v[92:95], v[28:31], v[120:123], v[92:95]
	v_mfma_f32_16x16x32_bf16 v[96:99], v[24:27], v[120:123], v[96:99]
	v_mfma_f32_16x16x32_bf16 v[84:87], v[56:59], v[120:123], v[84:87]
	v_mfma_f32_16x16x32_bf16 v[68:71], v[60:63], v[120:123], v[68:71]
	ds_read_b128 v[136:139], v80 offset:128
	v_mfma_f32_16x16x32_bf16 v[112:115], v[28:31], v[116:119], v[112:115]
	v_mfma_f32_16x16x32_bf16 v[108:111], v[24:27], v[116:119], v[108:111]
	v_mfma_f32_16x16x32_bf16 v[104:107], v[56:59], v[116:119], v[104:107]
	v_mfma_f32_16x16x32_bf16 v[100:103], v[60:63], v[116:119], v[100:103]
	ds_read_b128 v[120:123], v83 offset:128
	ds_read_b128 v[60:63], v217 offset:288
	ds_read_b128 v[56:59], v217 offset:320
	v_mfma_f32_16x16x32_bf16 v[92:95], v[32:35], v[152:155], v[92:95]
	v_mfma_f32_16x16x32_bf16 v[96:99], v[36:39], v[152:155], v[96:99]
	v_mfma_f32_16x16x32_bf16 v[84:87], v[28:31], v[152:155], v[84:87]
	v_mfma_f32_16x16x32_bf16 v[68:71], v[24:27], v[152:155], v[68:71]
	ds_read_b128 v[132:135], v80 offset:192
	v_mfma_f32_16x16x32_bf16 v[112:115], v[32:35], v[148:151], v[112:115]
	v_mfma_f32_16x16x32_bf16 v[108:111], v[36:39], v[148:151], v[108:111]
	v_mfma_f32_16x16x32_bf16 v[104:107], v[28:31], v[148:151], v[104:107]
	v_mfma_f32_16x16x32_bf16 v[100:103], v[24:27], v[148:151], v[100:103]
	ds_read_b128 v[116:119], v83 offset:192
	ds_read_b128 v[24:27], v217 offset:352
	ds_read_b128 v[28:31], v217 offset:384
	ds_read_b128 v[36:39], v217 offset:416
	ds_read_b128 v[32:35], v217 offset:448
	s_add_i32 s0, s71, 3
	s_cmp_ge_i32 s0, s87
	s_cbranch_scc1 .LBB0_434
	s_and_b32 s0, s0, 4
	s_and_b32 s1, s70, 3
	s_or_b32 s0, s0, s1
	s_mulk_i32 s0, 0x1200
	v_add_u32_e32 v80, s0, v157
	s_waitcnt vmcnt(0)
	ds_write2_b32 v80, v230, v231 offset1:32
	ds_write2_b32 v80, v238, v239 offset0:64 offset1:96

; #define CONV_TAIL() if (step + CONV_GRP < nsteps) CONV_STOREWIN(step + CONV_GRP); if ((step & 1) == 1 || step + 1 == nsteps) __syncthreads()
; #define CONV_DS(x) ({ int t_ = (x); LAUNDER_S(t_); t_; })
; __device__ __forceinline__ void conv_item(const Params& P, int slice, int item, LAS unsigned char* lds) {
;     ...
;     for (int d = CONV_DS(hi0 + 1); d <= hi1 - hw; ++d) { CONV_HEADT(); CONV_TILESTEP(1, CONV_BPH(1, 0, d + 1), CONV_BPH(1, 1, d + 1), 1, CONV_WB(step + 1), 3, 1); CONV_TAIL(); }
.LBB0_439:
	s_add_i32 s17, s61, s16
	v_lshl_add_u32 v240, v82, 1, v227
	global_load_dword v230, v240, s[8:9] offset:-2048
	global_load_dword v231, v240, s[8:9] offset:-1920
	global_load_dword v238, v240, s[8:9] offset:-1792
	global_load_dword v239, v240, s[8:9] offset:-1664
	v_add_u32_e32 v154, s30, v83
	s_add_i32 s0, s17, 1
	s_and_b32 s0, s0, 7
	s_mulk_i32 s0, 0x1200
	s_waitcnt lgkmcnt(1)
	v_mfma_f32_16x16x32_bf16 v[0:3], v[72:75], v[144:147], v[92:95]
	v_mfma_f32_16x16x32_bf16 v[4:7], v[64:67], v[144:147], v[96:99]
	v_mfma_f32_16x16x32_bf16 v[84:87], v[88:91], v[144:147], v[84:87]
	v_mfma_f32_16x16x32_bf16 v[68:71], v[76:79], v[144:147], v[68:71]
	s_waitcnt lgkmcnt(0)
	v_mfma_f32_16x16x32_bf16 v[92:95], v[72:75], v[128:131], v[112:115]
	v_mfma_f32_16x16x32_bf16 v[0:3], v[56:59], v[140:143], v[0:3]
	v_mfma_f32_16x16x32_bf16 v[92:95], v[56:59], v[124:127], v[92:95]
	v_mfma_f32_16x16x32_bf16 v[0:3], v[28:31], v[136:139], v[0:3]
	v_mfma_f32_16x16x32_bf16 v[96:99], v[28:31], v[120:123], v[92:95]
	v_mfma_f32_16x16x32_bf16 v[92:95], v[32:35], v[132:135], v[0:3]
	v_mfma_f32_16x16x32_bf16 v[112:115], v[32:35], v[116:119], v[96:99]
	v_mfma_f32_16x16x32_bf16 v[96:99], v[64:67], v[128:131], v[108:111]
	s_nop 3
	v_mfma_f32_16x16x32_bf16 v[88:91], v[88:91], v[128:131], v[104:107]
	v_mfma_f32_16x16x32_bf16 v[84:87], v[72:75], v[140:143], v[84:87]
	v_mfma_f32_16x16x32_bf16 v[72:75], v[72:75], v[124:127], v[88:91]
	v_mfma_f32_16x16x32_bf16 v[76:79], v[76:79], v[128:131], v[100:103]
	v_mfma_f32_16x16x32_bf16 v[84:87], v[56:59], v[136:139], v[84:87]
	v_mfma_f32_16x16x32_bf16 v[56:59], v[56:59], v[120:123], v[72:75]
	v_mfma_f32_16x16x32_bf16 v[84:87], v[28:31], v[132:135], v[84:87]
	v_mfma_f32_16x16x32_bf16 v[104:107], v[28:31], v[116:119], v[56:59]
	s_nop 1
	s_nop 0
	v_mov_b32_e32 v72, s29
	v_mfma_f32_16x16x32_bf16 v[2:5], v[60:63], v[140:143], v[4:7]
	v_mfma_f32_16x16x32_bf16 v[56:59], v[60:63], v[124:127], v[96:99]
	v_mfma_f32_16x16x32_bf16 v[2:5], v[24:27], v[136:139], v[2:5]
	v_mfma_f32_16x16x32_bf16 v[56:59], v[24:27], v[120:123], v[56:59]
	v_mfma_f32_16x16x32_bf16 v[96:99], v[36:39], v[132:135], v[2:5]
	v_mfma_f32_16x16x32_bf16 v[2:5], v[64:67], v[140:143], v[68:71]
	v_mfma_f32_16x16x32_bf16 v[108:111], v[36:39], v[116:119], v[56:59]
	v_mfma_f32_16x16x32_bf16 v[56:59], v[64:67], v[124:127], v[76:79]
	v_mfma_f32_16x16x32_bf16 v[2:5], v[60:63], v[136:139], v[2:5]
	v_mfma_f32_16x16x32_bf16 v[68:71], v[24:27], v[132:135], v[2:5]
	s_nop 6
	v_mfma_f32_16x16x32_bf16 v[56:59], v[60:63], v[120:123], v[56:59]
	v_mfma_f32_16x16x32_bf16 v[100:103], v[24:27], v[116:119], v[56:59]
	s_nop 6
	v_cmp_gt_u32_e32 vcc, s61, v83
	s_nop 1
	v_cndmask_b32_e32 v136, v72, v149, vcc
	ds_read_b128 v[140:143], v136 offset:64
	ds_read_b128 v[144:147], v136
	ds_read_b128 v[132:135], v136 offset:192
	ds_read_b128 v[136:139], v136 offset:128
	v_add_u32_e32 v155, s0, v243
	v_cmp_gt_u32_e64 s[0:1], s61, v154
	s_nop 1
	v_cndmask_b32_e64 v74, v72, v148, s[0:1]
	ds_read_b128 v[88:91], v155 offset:192
	ds_read_b128 v[124:127], v74 offset:64
	ds_read_b128 v[120:123], v74 offset:128
	ds_read_b128 v[128:131], v74
	ds_read_b128 v[116:119], v74 offset:192
	ds_read_b128 v[72:75], v155 offset:256
	ds_read_b128 v[32:35], v155 offset:448
	ds_read_b128 v[76:79], v155 offset:160
	ds_read_b128 v[28:31], v155 offset:384
	ds_read_b128 v[64:67], v155 offset:224
	ds_read_b128 v[36:39], v155 offset:416
	ds_read_b128 v[24:27], v155 offset:352
	ds_read_b128 v[60:63], v155 offset:288
	ds_read_b128 v[56:59], v155 offset:320
	s_add_i32 s0, s17, 4
	s_cmp_ge_i32 s0, s87
	s_cbranch_scc1 .LBB0_441
	s_and_b32 s0, s0, 4
	s_and_b32 s1, s17, 3
	s_or_b32 s0, s0, s1
	s_mulk_i32 s0, 0x1200
	v_add_u32_e32 v80, s0, v157
	s_waitcnt vmcnt(0)
	ds_write2_b32 v80, v230, v231 offset1:32
	ds_write2_b32 v80, v238, v239 offset0:64 offset1:96

; #define CONV_TAIL() if (step + CONV_GRP < nsteps) CONV_STOREWIN(step + CONV_GRP); if ((step & 1) == 1 || step + 1 == nsteps) __syncthreads()
; #define CONV_DS(x) ({ int t_ = (x); LAUNDER_S(t_); t_; })
; __device__ __forceinline__ void conv_item(const Params& P, int slice, int item, LAS unsigned char* lds) {
;     ...
;     for (int d = CONV_DS(hi1 - hw + 1); d <= hi1; ++d) { CONV_HEADT(); CONV_TILESTEP(1, CONV_BPH(1, 0, d + 1), CONV_BPH(1, 1, d + 1), 1, CONV_WB(step + 1), 2, 1); CONV_TAIL(); }
.LBB0_446:
	s_add_i32 s17, s61, s16
	v_lshl_add_u32 v240, v82, 1, v227
	global_load_dword v230, v240, s[8:9] offset:-2048
	global_load_dword v231, v240, s[8:9] offset:-1920
	global_load_dword v238, v240, s[8:9] offset:-1792
	global_load_dword v239, v240, s[8:9] offset:-1664
	s_add_i32 s0, s17, 1
	s_and_b32 s0, s0, 7
	s_mulk_i32 s0, 0x1200
	s_waitcnt lgkmcnt(0)
	v_mfma_f32_16x16x32_bf16 v[2:5], v[72:75], v[128:131], v[112:115]
	v_mfma_f32_16x16x32_bf16 v[108:111], v[64:67], v[128:131], v[108:111]
	v_mfma_f32_16x16x32_bf16 v[88:91], v[88:91], v[128:131], v[104:107]
	v_mfma_f32_16x16x32_bf16 v[76:79], v[76:79], v[128:131], v[100:103]
	v_mfma_f32_16x16x32_bf16 v[2:5], v[56:59], v[124:127], v[2:5]
	v_mfma_f32_16x16x32_bf16 v[100:103], v[60:63], v[124:127], v[108:111]
	v_mfma_f32_16x16x32_bf16 v[72:75], v[72:75], v[124:127], v[88:91]
	v_mfma_f32_16x16x32_bf16 v[64:67], v[64:67], v[124:127], v[76:79]
	v_mfma_f32_16x16x32_bf16 v[4:7], v[28:31], v[120:123], v[2:5]
	v_mfma_f32_16x16x32_bf16 v[76:79], v[24:27], v[120:123], v[100:103]
	v_mfma_f32_16x16x32_bf16 v[60:63], v[60:63], v[120:123], v[64:67]
	v_add_u32_e32 v133, s0, v243
	v_mfma_f32_16x16x32_bf16 v[112:115], v[32:35], v[116:119], v[4:7]
	v_mfma_f32_16x16x32_bf16 v[100:103], v[24:27], v[116:119], v[60:63]
	v_cmp_gt_u32_e64 s[0:1], s61, v83
	s_nop 1
	v_mov_b32_e32 v5, s29
	s_nop 0
	s_nop 1
	v_cndmask_b32_e64 v62, v5, v132, s[0:1]
	v_mfma_f32_16x16x32_bf16 v[72:75], v[56:59], v[120:123], v[72:75]
	v_mfma_f32_16x16x32_bf16 v[108:111], v[36:39], v[116:119], v[76:79]
	v_mfma_f32_16x16x32_bf16 v[104:107], v[28:31], v[116:119], v[72:75]
	ds_read_b128 v[116:119], v62 offset:192
	ds_read_b128 v[128:131], v62
	ds_read_b128 v[124:127], v62 offset:64
	ds_read_b128 v[120:123], v62 offset:128
	ds_read_b128 v[60:63], v133 offset:288
	ds_read_b128 v[56:59], v133 offset:320
	ds_read_b128 v[32:35], v133 offset:448
	ds_read_b128 v[24:27], v133 offset:352
	ds_read_b128 v[28:31], v133 offset:384
	ds_read_b128 v[36:39], v133 offset:416
	ds_read_b128 v[76:79], v133 offset:160
	ds_read_b128 v[88:91], v133 offset:192
	ds_read_b128 v[64:67], v133 offset:224
	ds_read_b128 v[72:75], v133 offset:256
	s_add_i32 s0, s17, 4
	s_cmp_ge_i32 s0, s87
	s_cbranch_scc1 .LBB0_448
	s_and_b32 s0, s0, 4
	s_and_b32 s1, s17, 3
	s_or_b32 s0, s0, s1
	s_mulk_i32 s0, 0x1200
	v_add_u32_e32 v80, s0, v157
	s_waitcnt vmcnt(0)
	ds_write2_b32 v80, v230, v231 offset1:32
	ds_write2_b32 v80, v238, v239 offset0:64 offset1:96
